# speedup vs baseline: 1.0165x; 1.0165x over previous
; #define LAS __attribute__((address_space(3)))
; __device__ __forceinline__ void attn_phase(LAS unsigned char* lds, bf16_t* Qb, const bf16_t* KVb, const bf16_t* GZ, const float* sinkp) {
;     ...
;         const int row0 = sbase + rb * 128 + 32 * (w >> 1), crr = lane >> 4, cch = lane & 15;
;         bf16x8 qf[8];
;         {
;             int qi = q, hi = h, cri = crr, chi = cch; asm volatile("" : "+v"(qi), "+v"(hi), "+v"(cri), "+v"(chi));
; #pragma unroll 4
;             for (int it = 0; it < 8; ++it) {
;                 const int rr = cri + 4 * it, grow = mu ? NREAL + seq * 16 + (rr & 15) : row0 + rr;
;                 const u32x4 v = *(const u32x4*)(Qb + (size_t)grow * 2048 + head * 128 + chi * 8);
;                 *(LAS u32x4*)(Wl + rr * 256 + ((chi ^ (rr & 15)) << 4)) = v;
;             }
; #pragma unroll
;             for (int ks = 0; ks < 8; ++ks) qf[ks] = *(const LAS bf16x8*)(Wl + qi * 256 + (((2 * ks + hi) ^ (qi & 15)) << 4));
;         }
;     ...
;             const bf16_t* kp0 = KVb + (size_t)(NREAL + seq * 16 + srow) * 1024 + kvh * 128 + sch * 8;
;             const bf16_t* kp1 = KVb + (size_t)(sbase + b0 * 128 + srow) * 1024 + kvh * 128 + sch * 8;
;             k0r[0] = *(const u32x4*)kp0; k0r[1] = *(const u32x4*)(kp0 + 32 * 1024); v0r[0] = *(const u32x4*)(kp0 + 512); v0r[1] = *(const u32x4*)(kp0 + 512 + 32 * 1024);
;             k1r[0] = *(const u32x4*)kp1; k1r[1] = *(const u32x4*)(kp1 + 32 * 1024); v1r[0] = *(const u32x4*)(kp1 + 512); v1r[1] = *(const u32x4*)(kp1 + 512 + 32 * 1024);
;             kreg[0] = *(const u32x4*)(kp1 + 64 * 1024); kreg[1] = *(const u32x4*)(kp1 + 96 * 1024); vreg[0] = *(const u32x4*)(kp1 + 512 + 64 * 1024); vreg[1] = *(const u32x4*)(kp1 + 512 + 96 * 1024);
.LBB0_162:
	s_lshl_b32 s36, s70, 11
	s_addk_i32 s36, 0x1800
	s_cmp_lg_u32 s70, 0
	s_cselect_b32 s71, s36, 0
	v_mov_b32_e32 v3, v149
	v_mov_b32_e32 v8, v159
	v_mov_b32_e32 v2, v148
	v_mov_b32_e32 v9, v158
	s_lshl_b32 s98, s58, 7
	s_lshl_b32 s36, s58, 8
	s_add_u32 s36, s16, s36
	v_add_u32_e32 v7, 4, v9
	s_addc_u32 s37, s17, 0
	v_lshlrev_b32_e32 v0, 3, v8
	s_lshl_b32 s60, s70, 4
	v_and_b32_e32 v5, 15, v7
	s_waitcnt vmcnt(3)
	v_bitop3_b32 v10, v9, 8, 15 bitop3:0x6c
	v_add_u32_e32 v11, 12, v9
	v_bitop3_b32 v7, v7, v8, 15 bitop3:0x6c
	v_ashrrev_i32_e32 v1, 31, v0
	s_addk_i32 s60, 0x6000
	s_waitcnt vmcnt(2)
	v_and_b32_e32 v12, 15, v11
	v_bitop3_b32 v13, v9, v8, 15 bitop3:0x6c
	s_waitcnt vmcnt(2)
	v_lshlrev_b32_e32 v14, 4, v7
	v_xor_b32_e32 v7, v10, v8
	v_bitop3_b32 v8, v11, v8, 15 bitop3:0x6c
	s_add_i32 s61, s73, s71
	v_lshl_add_u64 v[0:1], v[0:1], 1, s[36:37]
	v_and_b32_e32 v6, 15, v9
	v_lshlrev_b32_e32 v13, 4, v13
	v_lshlrev_b32_e32 v10, 4, v7
	v_or_b32_e32 v7, s60, v12
	v_lshlrev_b32_e32 v8, 4, v8
	v_lshlrev_b32_e32 v12, 8, v9
	s_add_i32 s36, s61, s66
	s_mov_b32 s59, 0
	v_or_b32_e32 v4, s60, v6
	v_or_b32_e32 v5, s60, v5
	v_bitop3_b32 v6, v6, s60, 8 bitop3:0xde
	v_add3_u32 v8, v12, v8, s65
	v_add_u32_e32 v9, s36, v9
	v_add3_u32 v10, v12, v10, s67
	v_add3_u32 v11, v12, v14, s68
	v_add3_u32 v12, v12, v13, s63
	v_mov_b32_e32 v60, v12
	v_mov_b32_e32 v61, v11
	v_mov_b32_e32 v62, v10
	v_mov_b32_e32 v63, v8
	v_add_u32_e32 v114, -12, v9
	v_cndmask_b32_e64 v112, v114, v4, s[4:5]
	v_ashrrev_i32_e32 v113, 31, v112
	v_lshlrev_b64 v[112:113], 12, v[112:113]
	v_lshl_add_u64 v[112:113], v[0:1], 0, v[112:113]
	global_load_dwordx4 v[112:115], v[112:113], off
	v_add_u32_e32 v118, -8, v9
	v_cndmask_b32_e64 v116, v118, v5, s[4:5]
	v_ashrrev_i32_e32 v117, 31, v116
	v_lshlrev_b64 v[116:117], 12, v[116:117]
	v_lshl_add_u64 v[116:117], v[0:1], 0, v[116:117]
	global_load_dwordx4 v[116:119], v[116:117], off
	v_add_u32_e32 v122, -4, v9
	v_cndmask_b32_e64 v120, v122, v6, s[4:5]
	v_ashrrev_i32_e32 v121, 31, v120
	v_lshlrev_b64 v[120:121], 12, v[120:121]
	v_lshl_add_u64 v[120:121], v[0:1], 0, v[120:121]
	global_load_dwordx4 v[120:123], v[120:121], off
	v_add_u32_e32 v126, 0, v9
	v_cndmask_b32_e64 v124, v126, v7, s[4:5]
	v_ashrrev_i32_e32 v125, 31, v124
	v_lshlrev_b64 v[124:125], 12, v[124:125]
	v_lshl_add_u64 v[124:125], v[0:1], 0, v[124:125]
	global_load_dwordx4 v[124:127], v[124:125], off
	v_add_u32_e32 v130, 4, v9
	v_cndmask_b32_e64 v128, v130, v4, s[4:5]
	v_ashrrev_i32_e32 v129, 31, v128
	v_lshlrev_b64 v[128:129], 12, v[128:129]
	v_lshl_add_u64 v[128:129], v[0:1], 0, v[128:129]
	global_load_dwordx4 v[128:131], v[128:129], off
	v_add_u32_e32 v134, 8, v9
	v_cndmask_b32_e64 v132, v134, v5, s[4:5]
	v_ashrrev_i32_e32 v133, 31, v132
	v_lshlrev_b64 v[132:133], 12, v[132:133]
	v_lshl_add_u64 v[132:133], v[0:1], 0, v[132:133]
	global_load_dwordx4 v[132:135], v[132:133], off
	v_add_u32_e32 v138, 12, v9
	v_cndmask_b32_e64 v136, v138, v6, s[4:5]
	v_ashrrev_i32_e32 v137, 31, v136
	v_lshlrev_b64 v[136:137], 12, v[136:137]
	v_lshl_add_u64 v[136:137], v[0:1], 0, v[136:137]
	global_load_dwordx4 v[136:139], v[136:137], off
	v_add_u32_e32 v142, 16, v9
	v_cndmask_b32_e64 v140, v142, v7, s[4:5]
	v_ashrrev_i32_e32 v141, 31, v140
	v_lshlrev_b64 v[140:141], 12, v[140:141]
	v_lshl_add_u64 v[140:141], v[0:1], 0, v[140:141]
	global_load_dwordx4 v[140:143], v[140:141], off
	s_max_i32 s36, s69, 1
	s_add_i32 s38, s36, -1
	s_and_b64 s[36:37], exec, s[4:5]
	s_cselect_b32 s70, 0, s38
	s_add_i32 s36, s69, 1
	s_min_i32 s38, s36, s72
	s_and_b64 s[36:37], exec, s[4:5]
	s_cselect_b32 s73, 0, s38
	s_mov_b32 s59, s99
	s_sub_i32 s72, s73, s70
	s_lshl_b64 s[36:37], s[58:59], 2
	s_add_u32 s36, s45, s36
	s_addc_u32 s37, s54, s37
	v_add_u32_e32 v0, s60, v169
	s_lshl_b32 s38, s70, 7
	v_ashrrev_i32_e32 v1, 31, v0
	s_add_i32 s38, s71, s38
	v_lshlrev_b64 v[0:1], 11, v[0:1]
	v_add_u32_e32 v4, s38, v169
	global_load_dword v16, v189, s[36:37]
	v_lshl_add_u64 v[0:1], s[50:51], 0, v[0:1]
	s_lshl_b32 s36, s3, 8
	s_mov_b32 s37, s99
	v_ashrrev_i32_e32 v5, 31, v4
	v_lshl_add_u64 v[0:1], v[0:1], 0, s[36:37]
	v_lshlrev_b64 v[4:5], 11, v[4:5]
	v_lshl_add_u64 v[0:1], v[0:1], 0, v[188:189]
	v_lshl_add_u64 v[4:5], s[50:51], 0, v[4:5]
	v_lshl_add_u64 v[4:5], v[4:5], 0, s[36:37]
	v_add_co_u32_e32 v18, vcc, s40, v0
	v_lshl_add_u64 v[38:39], v[4:5], 0, v[188:189]
	s_nop 0
	v_addc_co_u32_e32 v19, vcc, 0, v1, vcc
	global_load_dwordx4 v[4:7], v[0:1], off
	global_load_dwordx4 v[8:11], v[0:1], off offset:1024
	global_load_dwordx4 v[12:15], v[18:19], off
	s_nop 0
	global_load_dwordx4 v[18:21], v[18:19], off offset:1024
	v_add_co_u32_e32 v0, vcc, s40, v38
	s_mov_b32 s36, 0x20000
	s_nop 0
	v_addc_co_u32_e32 v1, vcc, 0, v39, vcc
	global_load_dwordx4 v[22:25], v[38:39], off
	global_load_dwordx4 v[26:29], v[38:39], off offset:1024
	global_load_dwordx4 v[30:33], v[0:1], off
	global_load_dwordx4 v[34:37], v[0:1], off offset:1024
	v_add_co_u32_e32 v0, vcc, s36, v38
	v_add_u32_e32 v17, 2, v3
	s_nop 0
	v_addc_co_u32_e32 v1, vcc, 0, v39, vcc
	v_add_co_u32_e32 v38, vcc, s41, v38
	v_add_u32_e32 v40, 8, v3
	s_nop 0
	v_addc_co_u32_e32 v39, vcc, 0, v39, vcc
	global_load_dwordx4 v[96:99], v[0:1], off
	global_load_dwordx4 v[100:103], v[0:1], off offset:1024
	global_load_dwordx4 v[104:107], v[38:39], off
	global_load_dwordx4 v[108:111], v[38:39], off offset:1024
	v_lshl_add_u32 v0, v2, 8, s63
	v_bitop3_b32 v1, v2, v3, 15 bitop3:0x6c
	v_add_u32_e32 v38, 4, v3
	v_add_u32_e32 v39, 6, v3
	v_add_u32_e32 v41, 10, v3
	v_add_u32_e32 v42, 12, v3
	v_add_u32_e32 v3, 14, v3
	v_lshl_add_u32 v1, v1, 4, v0
	v_bitop3_b32 v17, v17, v2, 15 bitop3:0x78
	v_bitop3_b32 v38, v38, v2, 15 bitop3:0x78
	v_bitop3_b32 v39, v39, v2, 15 bitop3:0x78
	v_bitop3_b32 v40, v40, v2, 15 bitop3:0x78
	v_bitop3_b32 v41, v41, v2, 15 bitop3:0x78
	v_bitop3_b32 v42, v42, v2, 15 bitop3:0x78
	v_bitop3_b32 v2, v3, v2, 15 bitop3:0x78
	v_lshl_add_u32 v3, v17, 4, v0
	v_lshl_add_u32 v17, v38, 4, v0
	v_lshl_add_u32 v38, v39, 4, v0
	v_lshl_add_u32 v39, v40, 4, v0
	v_lshl_add_u32 v40, v41, 4, v0
	v_lshl_add_u32 v41, v42, 4, v0
	v_lshl_add_u32 v0, v2, 4, v0
	s_waitcnt vmcnt(20)
	ds_write_b128 v60, v[112:115]
	s_waitcnt vmcnt(19)
	ds_write_b128 v61, v[116:119]
	s_waitcnt vmcnt(18)
	ds_write_b128 v62, v[120:123]
	s_waitcnt vmcnt(17)
	ds_write_b128 v63, v[124:127]
	s_waitcnt vmcnt(16)
	ds_write_b128 v60, v[128:131] offset:4096
	s_waitcnt vmcnt(15)
	ds_write_b128 v61, v[132:135] offset:4096
	s_waitcnt vmcnt(14)
	ds_write_b128 v62, v[136:139] offset:4096
	s_waitcnt vmcnt(13)
	ds_write_b128 v63, v[140:143] offset:4096
	ds_read_b128 v[112:115], v1
	ds_read_b128 v[116:119], v3
	ds_read_b128 v[120:123], v17
	ds_read_b128 v[124:127], v38
	ds_read_b128 v[128:131], v39
	ds_read_b128 v[132:135], v40
	ds_read_b128 v[136:139], v41
	ds_read_b128 v[140:143], v0
	s_cmp_gt_i32 s72, -2
	s_waitcnt lgkmcnt(0)
	s_barrier
; #define LAS __attribute__((address_space(3)))
; __device__ __forceinline__ void attn_phase(LAS unsigned char* lds, bf16_t* Qb, const bf16_t* KVb, const bf16_t* GZ, const float* sinkp) {
;     ...
;             __syncthreads();
;             *(LAS u32x4*)(Kt + soff) = k0r[0]; *(LAS u32x4*)(Kt + soff + 8192) = k0r[1]; *(LAS u32x4*)(Vt + soff) = v0r[0]; *(LAS u32x4*)(Vt + soff + 8192) = v0r[1];
;             *(LAS u32x4*)(Kt + 32768 + soff) = k1r[0]; *(LAS u32x4*)(Kt + 32768 + soff + 8192) = k1r[1]; *(LAS u32x4*)(Vt + 32768 + soff) = v1r[0]; *(LAS u32x4*)(Vt + 32768 + soff + 8192) = v1r[1];
;         }
;         for (int i = 0; i < ntiles; ++i) {
;             __syncthreads();
;             if (i >= 1 && i + 1 < ntiles) {
;                 const unsigned wb = ((i + 1) & 1) * 32768u;
;                 *(LAS u32x4*)(Kt + wb + soff) = kreg[0]; *(LAS u32x4*)(Kt + wb + soff + 8192) = kreg[1];
;                 *(LAS u32x4*)(Vt + wb + soff) = vreg[0]; *(LAS u32x4*)(Vt + wb + soff + 8192) = vreg[1];
;                 if (i + 2 < ntiles) {
;                     const int krow0 = sbase + (b0 + ((i + 1) >> 1)) * 128 + 64 * ((i + 1) & 1);
;                     const bf16_t* kp = KVb + (size_t)(krow0 + srow) * 1024 + kvh * 128 + sch * 8;
;                     kreg[0] = *(const u32x4*)kp; kreg[1] = *(const u32x4*)(kp + 32 * 1024); vreg[0] = *(const u32x4*)(kp + 512); vreg[1] = *(const u32x4*)(kp + 512 + 32 * 1024);
;                 }
;             }
;             const unsigned rb_off = (i & 1) * 32768u;
;             LAS unsigned char* Kc = Kt + rb_off; LAS unsigned char* Vc = Vt + rb_off;
;             if (i == 0) {
;                 f32x16 s0;
; #pragma unroll
;                 for (int r = 0; r < 16; ++r) s0[r] = 0.f;
; #pragma unroll
;                 for (int ks = 0; ks < 8; ++ks) {
;                     const bf16x8 k0 = *(const LAS bf16x8*)(Kc + kaddr[ks]);
;                     s0 = __builtin_amdgcn_mfma_f32_32x32x16_bf16(k0, qf[ks], s0, 0, 0, 0);
;                 }
;                 float mx = fmaxf(fmaxf(fmaxf(s0[0], s0[1]), fmaxf(s0[2], s0[3])), fmaxf(fmaxf(s0[4], s0[5]), fmaxf(s0[6], s0[7])));
;                 mx = fmaxf(mx, __shfl_xor(mx, 32));
;                 const float m_new = fmaxf(m_run, mx * SC), alpha = __builtin_amdgcn_exp2f(m_run - m_new);
;                 m_run = m_new;
;                 float rs = 0.f;
; #pragma unroll
	s_waitcnt vmcnt(11)
	ds_write_b128 v171, v[4:7]
	s_waitcnt vmcnt(10)
	ds_write_b128 v171, v[8:11] offset:16384
	s_waitcnt vmcnt(9)
	ds_write_b128 v171, v[12:15] offset:8192
	s_waitcnt vmcnt(8)
	ds_write_b128 v171, v[18:21] offset:24576
	s_waitcnt vmcnt(7)
	ds_write_b128 v171, v[22:25] offset:32768
	s_waitcnt vmcnt(5)
	ds_write_b128 v171, v[30:33] offset:40960
	ds_write_b128 v171, v[26:29] offset:49152
	s_waitcnt vmcnt(4)
	ds_write_b128 v171, v[34:37] offset:57344
	s_cbranch_scc0 .LBB0_181
	v_add_u32_e32 v0, 0, v150
	s_waitcnt lgkmcnt(0)
	s_barrier
	ds_read_b128 v[0:3], v0
	v_add_u32_e32 v4, 0, v151
	ds_read_b128 v[18:21], v4
	v_add_u32_e32 v17, 0, v152
	s_mov_b32 s36, 0x3fb8aa3b
	s_cmp_lt_i32 s72, 0
	s_waitcnt lgkmcnt(1)
	v_mfma_f32_32x32x16_bf16 v[0:15], v[0:3], v[112:115], 0
	s_waitcnt lgkmcnt(0)
	v_mfma_f32_32x32x16_bf16 v[0:15], v[18:21], v[116:119], v[0:15]
	ds_read_b128 v[18:21], v17
	v_add_u32_e32 v17, 0, v153
	ds_read_b128 v[22:25], v17
	v_add_u32_e32 v17, 0, v154
	s_waitcnt lgkmcnt(1)
	v_mfma_f32_32x32x16_bf16 v[0:15], v[18:21], v[120:123], v[0:15]
	ds_read_b128 v[18:21], v17
	v_add_u32_e32 v17, 0, v155
	s_waitcnt lgkmcnt(1)
	v_mfma_f32_32x32x16_bf16 v[0:15], v[22:25], v[124:127], v[0:15]
	ds_read_b128 v[22:25], v17
	v_add_u32_e32 v17, 0, v156
	s_waitcnt lgkmcnt(1)
	v_mfma_f32_32x32x16_bf16 v[0:15], v[18:21], v[128:131], v[0:15]
	ds_read_b128 v[18:21], v17
	v_add_u32_e32 v17, 0, v157
	s_waitcnt lgkmcnt(1)
	v_mfma_f32_32x32x16_bf16 v[0:15], v[22:25], v[132:135], v[0:15]
	ds_read_b128 v[22:25], v17
	v_xor_b32_e32 v17, 32, v232
	s_waitcnt lgkmcnt(1)
	v_mfma_f32_32x32x16_bf16 v[0:15], v[18:21], v[136:139], v[0:15]
	v_and_b32_e32 v18, 64, v232
	v_add_u32_e32 v18, 64, v18
	v_cmp_lt_i32_e32 vcc, v17, v18
	s_nop 1
	v_cndmask_b32_e32 v17, v232, v17, vcc
	v_lshlrev_b32_e32 v172, 2, v17
	s_waitcnt lgkmcnt(0)
	v_mfma_f32_32x32x16_bf16 v[0:15], v[22:25], v[140:143], v[0:15]
	s_nop 11
	v_max_f32_e32 v8, v1, v1
	v_max_f32_e32 v9, v0, v0
	v_max_f32_e32 v10, v3, v3
	v_max_f32_e32 v11, v2, v2
	v_max_f32_e32 v12, v7, v7
	v_max_f32_e32 v13, v6, v6
	v_max_f32_e32 v8, v9, v8
	v_max_f32_e32 v9, v11, v10
	v_max_f32_e32 v10, v13, v12
	v_max3_f32 v10, v4, v5, v10
	v_max3_f32 v8, v8, v9, v10
	ds_bpermute_b32 v9, v172, v8
	v_mul_f32_e32 v10, 0x3fb8aa3b, v16
	v_add_u32_e32 v11, 0, v161
	v_add_u32_e32 v12, 0, v162
	s_waitcnt lgkmcnt(0)
	v_max_f32_e32 v9, v9, v9
	v_max_f32_e32 v8, v8, v9
	v_mul_f32_e32 v8, 0x3e0293ee, v8
	v_max_f32_e32 v176, v10, v8
	v_fma_f32 v0, v0, s82, -v176
	v_fma_f32 v1, v1, s82, -v176
	v_fma_f32 v2, v2, s82, -v176
	v_fma_f32 v3, v3, s82, -v176
	v_fma_f32 v4, v4, s82, -v176
	v_fma_f32 v5, v5, s82, -v176
	v_fma_f32 v6, v6, s82, -v176
	v_fma_f32 v7, v7, s82, -v176
	v_exp_f32_e32 v13, v0
	v_exp_f32_e32 v14, v1
	v_exp_f32_e32 v15, v2
	v_exp_f32_e32 v65, v3
	v_exp_f32_e32 v66, v4
	v_exp_f32_e32 v67, v5
	v_exp_f32_e32 v68, v6
	v_exp_f32_e32 v69, v7
	v_cvt_pk_bf16_f32 v0, v13, v14
	v_cvt_pk_bf16_f32 v1, v15, v65
	v_cvt_pk_bf16_f32 v2, v66, v67
	v_cvt_pk_bf16_f32 v3, v68, v69
	ds_read_b64_tr_b16 v[4:5], v11 offset:16384
	ds_read_b64_tr_b16 v[6:7], v12 offset:16384
	v_add_u32_e32 v8, 0, v163
	v_add_u32_e32 v10, 0, v164
	ds_read_b64_tr_b16 v[8:9], v8 offset:16384
	ds_read_b64_tr_b16 v[10:11], v10 offset:16384
	s_waitcnt lgkmcnt(2)
	v_mfma_f32_32x32x16_bf16 v[48:63], v[4:7], v[0:3], 0
	v_add_u32_e32 v4, 0, v165
	v_add_u32_e32 v6, 0, v166
	ds_read_b64_tr_b16 v[4:5], v4 offset:16384
	ds_read_b64_tr_b16 v[6:7], v6 offset:16384
	v_add_u32_e32 v12, 0, v167
	v_add_f32_e32 v13, 0, v13
	s_waitcnt lgkmcnt(2)
	v_mfma_f32_32x32x16_bf16 v[32:47], v[8:11], v[0:3], 0
	v_add_u32_e32 v10, 0, v168
	v_fma_f32 v8, v16, s36, -v176
	v_exp_f32_e32 v70, v8
	ds_read_b64_tr_b16 v[8:9], v12 offset:16384
	ds_read_b64_tr_b16 v[10:11], v10 offset:16384
	v_add_f32_e32 v12, v14, v13
	s_waitcnt lgkmcnt(2)
	v_mfma_f32_32x32x16_bf16 v[16:31], v[4:7], v[0:3], 0
	v_add_f32_e32 v4, v15, v12
	v_add_f32_e32 v4, v65, v4
	v_add_f32_e32 v4, v66, v4
	v_add_f32_e32 v4, v67, v4
	v_add_f32_e32 v4, v68, v4
	v_add_f32_e32 v65, v69, v4
	ds_bpermute_b32 v66, v172, v65
	s_waitcnt lgkmcnt(1)
	v_mfma_f32_32x32x16_bf16 v[0:15], v[8:11], v[0:3], 0
	s_waitcnt lgkmcnt(0)
	v_add_f32_e32 v65, v65, v66
	v_add_f32_e32 v173, v70, v65
	s_cbranch_scc1 .LBB0_183
	s_lshl_b32 s3, s3, 7
	s_lshl_b32 s36, s3, 1
	s_mov_b32 s37, s99
	v_lshl_add_u64 v[146:147], v[144:145], 0, s[36:37]
	s_lshl_b32 s3, s73, 1
	s_lshl_b32 s36, s70, 1
	v_add_u32_e32 v174, s71, v169
	s_lshl_b32 s71, s72, 1
	s_sub_i32 s73, s3, s36
	s_add_i32 s72, s71, 3
	v_add_u32_e32 v175, 0x70, v64
	s_add_i32 s73, s73, 2
	s_mov_b32 s3, 0
	s_mov_b32 s75, 0x8000

; __device__ __forceinline__ unsigned cvt_pk_bf16(float lo, float hi) { unsigned r; asm volatile("v_cvt_pk_bf16_f32 %0, %1, %2" : "=v"(r) : "v"(lo), "v"(hi)); return r; }
; #define LAS __attribute__((address_space(3)))
; __device__ __forceinline__ void attn_phase(LAS unsigned char* lds, bf16_t* Qb, const bf16_t* KVb, const bf16_t* GZ, const float* sinkp) {
;     ...
;         const float inv = 1.f / l_run;
;         int qo = q, ho = h, cro = crr, cho = cch; asm volatile("" : "+v"(qo), "+v"(ho), "+v"(cro), "+v"(cho));
; #pragma unroll
;         for (int dt = 0; dt < 4; ++dt)
; #pragma unroll
;             for (int g4 = 0; g4 < 4; ++g4) {
;                 u32x2 ov; ov.x = cvt_pk_bf16(o[dt][4 * g4] * inv, o[dt][4 * g4 + 1] * inv); ov.y = cvt_pk_bf16(o[dt][4 * g4 + 2] * inv, o[dt][4 * g4 + 3] * inv);
;                 *(LAS u32x2*)(Wl + qo * 256 + (((4 * dt + g4) ^ (qo & 15)) << 4) + 8 * ho) = ov;
;             }
; #pragma unroll 2
;         for (int it = 0; it < 8; ++it) {
;             const int rr = cro + 4 * it, grow = mu ? NREAL + seq * 16 + (rr & 15) : row0 + rr;
;             const u32x4 ovv = *(const LAS u32x4*)(Wl + rr * 256 + ((cho ^ (rr & 15)) << 4));
;             const size_t goff = (size_t)grow * 2048 + head * 128 + cho * 8;
;             const u32x4 gz = *(const u32x4*)(GZ + goff);
;             float fo[8], fg[8]; unpack8(ovv, fo); unpack8(gz, fg);
;             u32x4 res; res.x = cvt_pk_bf16(fo[0] * fg[0], fo[1] * fg[1]); res.y = cvt_pk_bf16(fo[2] * fg[2], fo[3] * fg[3]); res.z = cvt_pk_bf16(fo[4] * fg[4], fo[5] * fg[5]); res.w = cvt_pk_bf16(fo[6] * fg[6], fo[7] * fg[7]);
;             if (!mu || (w < 4 && rr < 16)) *(u32x4*)(Qb + goff) = res;
;         }
.LBB0_183:
	v_div_scale_f32 v64, s[6:7], v173, v173, 1.0
	v_rcp_f32_e32 v65, v64
	v_div_scale_f32 v66, vcc, 1.0, v173, 1.0
	s_movk_i32 s3, 0x50
	v_fma_f32 v67, -v64, v65, 1.0
	v_fmac_f32_e32 v65, v67, v65
	v_mul_f32_e32 v67, v66, v65
	v_fma_f32 v68, -v64, v67, v66
	v_fmac_f32_e32 v67, v68, v65
	v_fma_f32 v64, -v64, v67, v66
	v_div_fmas_f32 v64, v64, v65, v67
	v_div_fixup_f32 v66, v64, v173, 1.0
	v_mov_b32_e32 v67, v149
	v_mov_b32_e32 v64, v159
	v_mov_b32_e32 v68, v148
	v_mov_b32_e32 v65, v158
	v_mul_f32_e32 v48, v48, v66
	v_mul_f32_e32 v49, v49, v66
	v_cvt_pk_bf16_f32 v48, v48, v49
	v_mul_f32_e32 v49, v50, v66
	v_mul_f32_e32 v50, v51, v66
	v_lshlrev_b32_e32 v69, 8, v68
	v_lshlrev_b32_e32 v67, 3, v67
	v_cvt_pk_bf16_f32 v49, v49, v50
	v_lshlrev_b32_e32 v50, 4, v68
	v_add3_u32 v67, s63, v69, v67
	v_and_b32_e32 v50, 0xf0, v50
	v_add_u32_e32 v51, v67, v50
	ds_write_b64 v51, v[48:49]
	v_mul_f32_e32 v48, v52, v66
	v_mul_f32_e32 v49, v53, v66
	v_cvt_pk_bf16_f32 v48, v48, v49
	v_mul_f32_e32 v49, v54, v66
	v_mul_f32_e32 v51, v55, v66
	v_cvt_pk_bf16_f32 v49, v49, v51
	v_xad_u32 v51, v50, 16, v67
	ds_write_b64 v51, v[48:49]
	v_mul_f32_e32 v48, v56, v66
	v_mul_f32_e32 v49, v57, v66
	v_cvt_pk_bf16_f32 v48, v48, v49
	v_mul_f32_e32 v49, v58, v66
	v_mul_f32_e32 v51, v59, v66
	v_cvt_pk_bf16_f32 v49, v49, v51
	v_xad_u32 v51, v50, 32, v67
	ds_write_b64 v51, v[48:49]
	v_mul_f32_e32 v48, v60, v66
	v_mul_f32_e32 v49, v61, v66
	v_cvt_pk_bf16_f32 v48, v48, v49
	v_mul_f32_e32 v49, v62, v66
	v_mul_f32_e32 v51, v63, v66
	v_cvt_pk_bf16_f32 v49, v49, v51
	v_xad_u32 v51, v50, 48, v67
	v_mul_f32_e32 v32, v32, v66
	v_mul_f32_e32 v33, v33, v66
	ds_write_b64 v51, v[48:49]
	v_cvt_pk_bf16_f32 v32, v32, v33
	v_mul_f32_e32 v33, v34, v66
	v_mul_f32_e32 v34, v35, v66
	v_cvt_pk_bf16_f32 v33, v33, v34
	v_xad_u32 v34, v50, 64, v67
	ds_write_b64 v34, v[32:33]
	v_mul_f32_e32 v32, v36, v66
	v_mul_f32_e32 v33, v37, v66
	v_cvt_pk_bf16_f32 v32, v32, v33
	v_mul_f32_e32 v33, v38, v66
	v_mul_f32_e32 v34, v39, v66
	v_cvt_pk_bf16_f32 v33, v33, v34
	v_xad_u32 v34, v50, s3, v67
	ds_write_b64 v34, v[32:33]
	v_mul_f32_e32 v32, v40, v66
	v_mul_f32_e32 v33, v41, v66
	v_cvt_pk_bf16_f32 v32, v32, v33
	v_mul_f32_e32 v33, v42, v66
	v_mul_f32_e32 v34, v43, v66
	v_cvt_pk_bf16_f32 v33, v33, v34
	v_xad_u32 v34, v50, s43, v67
	ds_write_b64 v34, v[32:33]
	v_mul_f32_e32 v32, v44, v66
	v_mul_f32_e32 v33, v45, v66
	v_cvt_pk_bf16_f32 v32, v32, v33
	v_mul_f32_e32 v33, v46, v66
	v_mul_f32_e32 v34, v47, v66
	s_movk_i32 s3, 0x70
	v_cvt_pk_bf16_f32 v33, v33, v34
	v_xad_u32 v34, v50, s3, v67
	v_mul_f32_e32 v16, v16, v66
	v_mul_f32_e32 v17, v17, v66
	ds_write_b64 v34, v[32:33]
	v_cvt_pk_bf16_f32 v16, v16, v17
	v_mul_f32_e32 v17, v18, v66
	v_mul_f32_e32 v18, v19, v66
	s_movk_i32 s3, 0x80
	v_cvt_pk_bf16_f32 v17, v17, v18
	v_xad_u32 v18, v50, s3, v67
	ds_write_b64 v18, v[16:17]
	v_mul_f32_e32 v16, v20, v66
	v_mul_f32_e32 v17, v21, v66
	v_cvt_pk_bf16_f32 v16, v16, v17
	v_mul_f32_e32 v17, v22, v66
	v_mul_f32_e32 v18, v23, v66
	s_movk_i32 s3, 0x90
	v_cvt_pk_bf16_f32 v17, v17, v18
	v_xad_u32 v18, v50, s3, v67
	ds_write_b64 v18, v[16:17]
	v_mul_f32_e32 v16, v24, v66
	v_mul_f32_e32 v17, v25, v66
	v_cvt_pk_bf16_f32 v16, v16, v17
	v_mul_f32_e32 v17, v26, v66
	v_mul_f32_e32 v18, v27, v66
	s_movk_i32 s3, 0xa0
	v_cvt_pk_bf16_f32 v17, v17, v18
	v_xad_u32 v18, v50, s3, v67
	ds_write_b64 v18, v[16:17]
	v_mul_f32_e32 v16, v28, v66
	v_mul_f32_e32 v17, v29, v66
	v_cvt_pk_bf16_f32 v16, v16, v17
	v_mul_f32_e32 v17, v30, v66
	v_mul_f32_e32 v18, v31, v66
	s_movk_i32 s3, 0xb0
	v_cvt_pk_bf16_f32 v17, v17, v18
	v_xad_u32 v18, v50, s3, v67
	v_mul_f32_e32 v0, v0, v66
	v_mul_f32_e32 v1, v1, v66
	ds_write_b64 v18, v[16:17]
	v_cvt_pk_bf16_f32 v0, v0, v1
	v_mul_f32_e32 v1, v2, v66
	v_mul_f32_e32 v2, v3, v66
	s_movk_i32 s3, 0xc0
	v_cvt_pk_bf16_f32 v1, v1, v2
	v_xad_u32 v2, v50, s3, v67
	ds_write_b64 v2, v[0:1]
	v_mul_f32_e32 v0, v4, v66
	v_mul_f32_e32 v1, v5, v66
	v_cvt_pk_bf16_f32 v0, v0, v1
	v_mul_f32_e32 v1, v6, v66
	v_mul_f32_e32 v2, v7, v66
	s_movk_i32 s3, 0xd0
	v_cvt_pk_bf16_f32 v1, v1, v2
	v_xad_u32 v2, v50, s3, v67
	ds_write_b64 v2, v[0:1]
	v_mul_f32_e32 v0, v8, v66
	v_mul_f32_e32 v1, v9, v66
	v_cvt_pk_bf16_f32 v0, v0, v1
	v_mul_f32_e32 v1, v10, v66
	v_mul_f32_e32 v2, v11, v66
	s_movk_i32 s3, 0xe0
	v_cvt_pk_bf16_f32 v1, v1, v2
	v_xad_u32 v2, v50, s3, v67
	ds_write_b64 v2, v[0:1]
	v_mul_f32_e32 v0, v12, v66
	v_mul_f32_e32 v1, v13, v66
	v_cvt_pk_bf16_f32 v0, v0, v1
	v_mul_f32_e32 v1, v14, v66
	v_mul_f32_e32 v2, v15, v66
	s_movk_i32 s3, 0xf0
	v_cvt_pk_bf16_f32 v1, v1, v2
	v_xad_u32 v2, v50, s3, v67
	ds_write_b64 v2, v[0:1]
	v_lshlrev_b32_e32 v0, 3, v64
	v_readlane_b32 s70, v255, 3
	v_ashrrev_i32_e32 v1, 31, v0
	s_add_i32 s61, s61, s64
	v_readlane_b32 s71, v255, 4
	v_lshl_add_u64 v[4:5], v[0:1], 0, s[98:99]
	v_lshl_add_u32 v8, v65, 8, s68
	v_add_u32_e32 v9, s61, v65
	v_add_u32_e32 v8, 0xfffffc00, v8
	v_add_u32_e32 v10, 0, v65
	v_and_b32_e32 v0, 15, v10
	v_or_b32_e32 v0, s60, v0
	v_add_u32_e32 v11, 0, v9
	v_cndmask_b32_e64 v0, v11, v0, s[4:5]
	v_ashrrev_i32_e32 v1, 31, v0
	v_lshlrev_b64 v[0:1], 11, v[0:1]
	v_lshl_add_u64 v[96:97], v[4:5], 0, v[0:1]
	v_lshl_add_u64 v[0:1], v[96:97], 1, s[48:49]
	global_load_dwordx4 v[24:27], v[0:1], off
	v_bitop3_b32 v12, v10, v64, 15 bitop3:0x6c
	v_lshl_add_u32 v12, v12, 4, v8
	ds_read_b128 v[112:115], v12
	v_add_u32_e32 v10, 4, v65
	v_and_b32_e32 v0, 15, v10
	v_or_b32_e32 v0, s60, v0
	v_add_u32_e32 v11, 4, v9
	v_cndmask_b32_e64 v0, v11, v0, s[4:5]
	v_ashrrev_i32_e32 v1, 31, v0
	v_lshlrev_b64 v[0:1], 11, v[0:1]
	v_lshl_add_u64 v[98:99], v[4:5], 0, v[0:1]
	v_lshl_add_u64 v[0:1], v[98:99], 1, s[48:49]
; __device__ __forceinline__ unsigned cvt_pk_bf16(float lo, float hi) { unsigned r; asm volatile("v_cvt_pk_bf16_f32 %0, %1, %2" : "=v"(r) : "v"(lo), "v"(hi)); return r; }
; #define LAS __attribute__((address_space(3)))
; __device__ __forceinline__ void attn_phase(LAS unsigned char* lds, bf16_t* Qb, const bf16_t* KVb, const bf16_t* GZ, const float* sinkp) {
;     ...
;         for (int it = 0; it < 8; ++it) {
;             const int rr = cro + 4 * it, grow = mu ? NREAL + seq * 16 + (rr & 15) : row0 + rr;
;             const u32x4 ovv = *(const LAS u32x4*)(Wl + rr * 256 + ((cho ^ (rr & 15)) << 4));
;             const size_t goff = (size_t)grow * 2048 + head * 128 + cho * 8;
;             const u32x4 gz = *(const u32x4*)(GZ + goff);
;             float fo[8], fg[8]; unpack8(ovv, fo); unpack8(gz, fg);
;             u32x4 res; res.x = cvt_pk_bf16(fo[0] * fg[0], fo[1] * fg[1]); res.y = cvt_pk_bf16(fo[2] * fg[2], fo[3] * fg[3]); res.z = cvt_pk_bf16(fo[4] * fg[4], fo[5] * fg[5]); res.w = cvt_pk_bf16(fo[6] * fg[6], fo[7] * fg[7]);
;             if (!mu || (w < 4 && rr < 16)) *(u32x4*)(Qb + goff) = res;
;         }
	global_load_dwordx4 v[28:31], v[0:1], off
	v_bitop3_b32 v12, v10, v64, 15 bitop3:0x6c
	v_lshl_add_u32 v12, v12, 4, v8
	ds_read_b128 v[116:119], v12 offset:1024
	v_add_u32_e32 v10, 8, v65
	v_and_b32_e32 v0, 15, v10
	v_or_b32_e32 v0, s60, v0
	v_add_u32_e32 v11, 8, v9
	v_cndmask_b32_e64 v0, v11, v0, s[4:5]
	v_ashrrev_i32_e32 v1, 31, v0
	v_lshlrev_b64 v[0:1], 11, v[0:1]
	v_lshl_add_u64 v[100:101], v[4:5], 0, v[0:1]
	v_lshl_add_u64 v[0:1], v[100:101], 1, s[48:49]
	global_load_dwordx4 v[32:35], v[0:1], off
	v_bitop3_b32 v12, v10, v64, 15 bitop3:0x6c
	v_lshl_add_u32 v12, v12, 4, v8
	ds_read_b128 v[120:123], v12 offset:2048
	v_add_u32_e32 v10, 12, v65
	v_and_b32_e32 v0, 15, v10
	v_or_b32_e32 v0, s60, v0
	v_add_u32_e32 v11, 12, v9
	v_cndmask_b32_e64 v0, v11, v0, s[4:5]
	v_ashrrev_i32_e32 v1, 31, v0
	v_lshlrev_b64 v[0:1], 11, v[0:1]
	v_lshl_add_u64 v[102:103], v[4:5], 0, v[0:1]
	v_lshl_add_u64 v[0:1], v[102:103], 1, s[48:49]
	global_load_dwordx4 v[36:39], v[0:1], off
	v_bitop3_b32 v12, v10, v64, 15 bitop3:0x6c
	v_lshl_add_u32 v12, v12, 4, v8
	ds_read_b128 v[124:127], v12 offset:3072
	v_add_u32_e32 v10, 16, v65
	v_and_b32_e32 v0, 15, v10
	v_or_b32_e32 v0, s60, v0
	v_add_u32_e32 v11, 16, v9
	v_cndmask_b32_e64 v0, v11, v0, s[4:5]
	v_ashrrev_i32_e32 v1, 31, v0
	v_lshlrev_b64 v[0:1], 11, v[0:1]
	v_lshl_add_u64 v[104:105], v[4:5], 0, v[0:1]
	v_lshl_add_u64 v[0:1], v[104:105], 1, s[48:49]
	global_load_dwordx4 v[40:43], v[0:1], off
	v_bitop3_b32 v12, v10, v64, 15 bitop3:0x6c
	v_lshl_add_u32 v12, v12, 4, v8
	ds_read_b128 v[128:131], v12 offset:4096
	v_add_u32_e32 v10, 20, v65
	v_and_b32_e32 v0, 15, v10
	v_or_b32_e32 v0, s60, v0
	v_add_u32_e32 v11, 20, v9
	v_cndmask_b32_e64 v0, v11, v0, s[4:5]
	v_ashrrev_i32_e32 v1, 31, v0
	v_lshlrev_b64 v[0:1], 11, v[0:1]
	v_lshl_add_u64 v[106:107], v[4:5], 0, v[0:1]
	v_lshl_add_u64 v[0:1], v[106:107], 1, s[48:49]
	global_load_dwordx4 v[44:47], v[0:1], off
	v_bitop3_b32 v12, v10, v64, 15 bitop3:0x6c
	v_lshl_add_u32 v12, v12, 4, v8
	ds_read_b128 v[132:135], v12 offset:5120
	v_add_u32_e32 v10, 24, v65
	v_and_b32_e32 v0, 15, v10
	v_or_b32_e32 v0, s60, v0
	v_add_u32_e32 v11, 24, v9
	v_cndmask_b32_e64 v0, v11, v0, s[4:5]
	v_ashrrev_i32_e32 v1, 31, v0
	v_lshlrev_b64 v[0:1], 11, v[0:1]
	v_lshl_add_u64 v[108:109], v[4:5], 0, v[0:1]
	v_lshl_add_u64 v[0:1], v[108:109], 1, s[48:49]
	global_load_dwordx4 v[48:51], v[0:1], off
	v_bitop3_b32 v12, v10, v64, 15 bitop3:0x6c
	v_lshl_add_u32 v12, v12, 4, v8
	ds_read_b128 v[136:139], v12 offset:6144
	v_add_u32_e32 v10, 28, v65
	v_and_b32_e32 v0, 15, v10
	v_or_b32_e32 v0, s60, v0
	v_add_u32_e32 v11, 28, v9
	v_cndmask_b32_e64 v0, v11, v0, s[4:5]
	v_ashrrev_i32_e32 v1, 31, v0
	v_lshlrev_b64 v[0:1], 11, v[0:1]
	v_lshl_add_u64 v[110:111], v[4:5], 0, v[0:1]
	v_lshl_add_u64 v[0:1], v[110:111], 1, s[48:49]
	global_load_dwordx4 v[52:55], v[0:1], off
	v_bitop3_b32 v12, v10, v64, 15 bitop3:0x6c
	v_lshl_add_u32 v12, v12, 4, v8
	ds_read_b128 v[140:143], v12 offset:7168
	s_waitcnt lgkmcnt(7)
	v_lshlrev_b32_e32 v16, 16, v112
	v_and_b32_e32 v112, 0xffff0000, v112
	v_lshlrev_b32_e32 v17, 16, v113
	v_and_b32_e32 v113, 0xffff0000, v113
	v_lshlrev_b32_e32 v18, 16, v114
	v_and_b32_e32 v114, 0xffff0000, v114
	v_lshlrev_b32_e32 v19, 16, v115
	v_and_b32_e32 v115, 0xffff0000, v115
	s_waitcnt vmcnt(7)
	v_lshlrev_b32_e32 v20, 16, v24
	v_and_b32_e32 v24, 0xffff0000, v24
	v_lshlrev_b32_e32 v21, 16, v25
	v_and_b32_e32 v25, 0xffff0000, v25
	v_lshlrev_b32_e32 v22, 16, v26
	v_and_b32_e32 v26, 0xffff0000, v26
	v_lshlrev_b32_e32 v23, 16, v27
	v_and_b32_e32 v27, 0xffff0000, v27
	v_mul_f32_e32 v0, v112, v24
	v_mul_f32_e32 v1, v113, v25
	v_mul_f32_e32 v2, v114, v26
	v_mul_f32_e32 v3, v115, v27
	v_mul_f32_e32 v16, v16, v20
	v_mul_f32_e32 v17, v17, v21
	v_mul_f32_e32 v18, v18, v22
	v_mul_f32_e32 v19, v19, v23
	v_cvt_pk_bf16_f32 v0, v16, v0
	v_cvt_pk_bf16_f32 v1, v17, v1
	v_cvt_pk_bf16_f32 v2, v18, v2
	v_cvt_pk_bf16_f32 v3, v19, v3
	v_add_u32_e32 v10, 0, v65
	v_cmp_lt_i32_e32 vcc, 15, v10
	s_or_b64 s[6:7], s[56:57], vcc
	s_and_b64 s[6:7], s[4:5], s[6:7]
	s_xor_b64 s[36:37], s[6:7], -1
	s_and_saveexec_b64 s[6:7], s[36:37]
	s_cbranch_execz .Lattn_ep_skip0
	v_lshl_add_u64 v[6:7], v[96:97], 1, s[16:17]
	global_store_dwordx4 v[6:7], v[0:3], off
.Lattn_ep_skip0:
	s_or_b64 exec, exec, s[6:7]
	s_waitcnt lgkmcnt(6)
	v_lshlrev_b32_e32 v16, 16, v116
	v_and_b32_e32 v116, 0xffff0000, v116
	v_lshlrev_b32_e32 v17, 16, v117
	v_and_b32_e32 v117, 0xffff0000, v117
	v_lshlrev_b32_e32 v18, 16, v118
	v_and_b32_e32 v118, 0xffff0000, v118
	v_lshlrev_b32_e32 v19, 16, v119
	v_and_b32_e32 v119, 0xffff0000, v119
	s_waitcnt vmcnt(6)
	v_lshlrev_b32_e32 v20, 16, v28
	v_and_b32_e32 v28, 0xffff0000, v28
	v_lshlrev_b32_e32 v21, 16, v29
	v_and_b32_e32 v29, 0xffff0000, v29
	v_lshlrev_b32_e32 v22, 16, v30
	v_and_b32_e32 v30, 0xffff0000, v30
	v_lshlrev_b32_e32 v23, 16, v31
	v_and_b32_e32 v31, 0xffff0000, v31
	v_mul_f32_e32 v0, v116, v28
	v_mul_f32_e32 v1, v117, v29
	v_mul_f32_e32 v2, v118, v30
	v_mul_f32_e32 v3, v119, v31
	v_mul_f32_e32 v16, v16, v20
	v_mul_f32_e32 v17, v17, v21
	v_mul_f32_e32 v18, v18, v22
	v_mul_f32_e32 v19, v19, v23
	v_cvt_pk_bf16_f32 v0, v16, v0
	v_cvt_pk_bf16_f32 v1, v17, v1
	v_cvt_pk_bf16_f32 v2, v18, v2
	v_cvt_pk_bf16_f32 v3, v19, v3
	v_add_u32_e32 v10, 4, v65
	v_cmp_lt_i32_e32 vcc, 15, v10
	s_or_b64 s[6:7], s[56:57], vcc
	s_and_b64 s[6:7], s[4:5], s[6:7]
	s_xor_b64 s[36:37], s[6:7], -1
	s_and_saveexec_b64 s[6:7], s[36:37]
	s_cbranch_execz .Lattn_ep_skip1
	v_lshl_add_u64 v[6:7], v[98:99], 1, s[16:17]
	global_store_dwordx4 v[6:7], v[0:3], off
; __device__ __forceinline__ unsigned cvt_pk_bf16(float lo, float hi) { unsigned r; asm volatile("v_cvt_pk_bf16_f32 %0, %1, %2" : "=v"(r) : "v"(lo), "v"(hi)); return r; }
; #define LAS __attribute__((address_space(3)))
; __device__ __forceinline__ void attn_phase(LAS unsigned char* lds, bf16_t* Qb, const bf16_t* KVb, const bf16_t* GZ, const float* sinkp) {
;     ...
;         for (int it = 0; it < 8; ++it) {
;             const int rr = cro + 4 * it, grow = mu ? NREAL + seq * 16 + (rr & 15) : row0 + rr;
;             const u32x4 ovv = *(const LAS u32x4*)(Wl + rr * 256 + ((cho ^ (rr & 15)) << 4));
;             const size_t goff = (size_t)grow * 2048 + head * 128 + cho * 8;
;             const u32x4 gz = *(const u32x4*)(GZ + goff);
;             float fo[8], fg[8]; unpack8(ovv, fo); unpack8(gz, fg);
;             u32x4 res; res.x = cvt_pk_bf16(fo[0] * fg[0], fo[1] * fg[1]); res.y = cvt_pk_bf16(fo[2] * fg[2], fo[3] * fg[3]); res.z = cvt_pk_bf16(fo[4] * fg[4], fo[5] * fg[5]); res.w = cvt_pk_bf16(fo[6] * fg[6], fo[7] * fg[7]);
;             if (!mu || (w < 4 && rr < 16)) *(u32x4*)(Qb + goff) = res;
;         }
.Lattn_ep_skip1:
	s_or_b64 exec, exec, s[6:7]
	s_waitcnt lgkmcnt(5)
	v_lshlrev_b32_e32 v16, 16, v120
	v_and_b32_e32 v120, 0xffff0000, v120
	v_lshlrev_b32_e32 v17, 16, v121
	v_and_b32_e32 v121, 0xffff0000, v121
	v_lshlrev_b32_e32 v18, 16, v122
	v_and_b32_e32 v122, 0xffff0000, v122
	v_lshlrev_b32_e32 v19, 16, v123
	v_and_b32_e32 v123, 0xffff0000, v123
	s_waitcnt vmcnt(5)
	v_lshlrev_b32_e32 v20, 16, v32
	v_and_b32_e32 v32, 0xffff0000, v32
	v_lshlrev_b32_e32 v21, 16, v33
	v_and_b32_e32 v33, 0xffff0000, v33
	v_lshlrev_b32_e32 v22, 16, v34
	v_and_b32_e32 v34, 0xffff0000, v34
	v_lshlrev_b32_e32 v23, 16, v35
	v_and_b32_e32 v35, 0xffff0000, v35
	v_mul_f32_e32 v0, v120, v32
	v_mul_f32_e32 v1, v121, v33
	v_mul_f32_e32 v2, v122, v34
	v_mul_f32_e32 v3, v123, v35
	v_mul_f32_e32 v16, v16, v20
	v_mul_f32_e32 v17, v17, v21
	v_mul_f32_e32 v18, v18, v22
	v_mul_f32_e32 v19, v19, v23
	v_cvt_pk_bf16_f32 v0, v16, v0
	v_cvt_pk_bf16_f32 v1, v17, v1
	v_cvt_pk_bf16_f32 v2, v18, v2
	v_cvt_pk_bf16_f32 v3, v19, v3
	v_add_u32_e32 v10, 8, v65
	v_cmp_lt_i32_e32 vcc, 15, v10
	s_or_b64 s[6:7], s[56:57], vcc
	s_and_b64 s[6:7], s[4:5], s[6:7]
	s_xor_b64 s[36:37], s[6:7], -1
	s_and_saveexec_b64 s[6:7], s[36:37]
	s_cbranch_execz .Lattn_ep_skip2
	v_lshl_add_u64 v[6:7], v[100:101], 1, s[16:17]
	global_store_dwordx4 v[6:7], v[0:3], off
.Lattn_ep_skip2:
	s_or_b64 exec, exec, s[6:7]
	s_waitcnt lgkmcnt(4)
	v_lshlrev_b32_e32 v16, 16, v124
	v_and_b32_e32 v124, 0xffff0000, v124
	v_lshlrev_b32_e32 v17, 16, v125
	v_and_b32_e32 v125, 0xffff0000, v125
	v_lshlrev_b32_e32 v18, 16, v126
	v_and_b32_e32 v126, 0xffff0000, v126
	v_lshlrev_b32_e32 v19, 16, v127
	v_and_b32_e32 v127, 0xffff0000, v127
	s_waitcnt vmcnt(4)
	v_lshlrev_b32_e32 v20, 16, v36
	v_and_b32_e32 v36, 0xffff0000, v36
	v_lshlrev_b32_e32 v21, 16, v37
	v_and_b32_e32 v37, 0xffff0000, v37
	v_lshlrev_b32_e32 v22, 16, v38
	v_and_b32_e32 v38, 0xffff0000, v38
	v_lshlrev_b32_e32 v23, 16, v39
	v_and_b32_e32 v39, 0xffff0000, v39
	v_mul_f32_e32 v0, v124, v36
	v_mul_f32_e32 v1, v125, v37
	v_mul_f32_e32 v2, v126, v38
	v_mul_f32_e32 v3, v127, v39
	v_mul_f32_e32 v16, v16, v20
	v_mul_f32_e32 v17, v17, v21
	v_mul_f32_e32 v18, v18, v22
	v_mul_f32_e32 v19, v19, v23
	v_cvt_pk_bf16_f32 v0, v16, v0
	v_cvt_pk_bf16_f32 v1, v17, v1
	v_cvt_pk_bf16_f32 v2, v18, v2
	v_cvt_pk_bf16_f32 v3, v19, v3
	v_add_u32_e32 v10, 12, v65
	v_cmp_lt_i32_e32 vcc, 15, v10
	s_or_b64 s[6:7], s[56:57], vcc
	s_and_b64 s[6:7], s[4:5], s[6:7]
	s_xor_b64 s[36:37], s[6:7], -1
	s_and_saveexec_b64 s[6:7], s[36:37]
	s_cbranch_execz .Lattn_ep_skip3
	v_lshl_add_u64 v[6:7], v[102:103], 1, s[16:17]
	global_store_dwordx4 v[6:7], v[0:3], off
.Lattn_ep_skip3:
	s_or_b64 exec, exec, s[6:7]
	s_waitcnt lgkmcnt(3)
	v_lshlrev_b32_e32 v16, 16, v128
	v_and_b32_e32 v128, 0xffff0000, v128
	v_lshlrev_b32_e32 v17, 16, v129
	v_and_b32_e32 v129, 0xffff0000, v129
	v_lshlrev_b32_e32 v18, 16, v130
	v_and_b32_e32 v130, 0xffff0000, v130
	v_lshlrev_b32_e32 v19, 16, v131
	v_and_b32_e32 v131, 0xffff0000, v131
	s_waitcnt vmcnt(3)
	v_lshlrev_b32_e32 v20, 16, v40
	v_and_b32_e32 v40, 0xffff0000, v40
	v_lshlrev_b32_e32 v21, 16, v41
	v_and_b32_e32 v41, 0xffff0000, v41
	v_lshlrev_b32_e32 v22, 16, v42
	v_and_b32_e32 v42, 0xffff0000, v42
	v_lshlrev_b32_e32 v23, 16, v43
	v_and_b32_e32 v43, 0xffff0000, v43
	v_mul_f32_e32 v0, v128, v40
	v_mul_f32_e32 v1, v129, v41
	v_mul_f32_e32 v2, v130, v42
	v_mul_f32_e32 v3, v131, v43
	v_mul_f32_e32 v16, v16, v20
	v_mul_f32_e32 v17, v17, v21
	v_mul_f32_e32 v18, v18, v22
	v_mul_f32_e32 v19, v19, v23
	v_cvt_pk_bf16_f32 v0, v16, v0
	v_cvt_pk_bf16_f32 v1, v17, v1
	v_cvt_pk_bf16_f32 v2, v18, v2
	v_cvt_pk_bf16_f32 v3, v19, v3
	v_add_u32_e32 v10, 16, v65
	v_cmp_lt_i32_e32 vcc, 15, v10
	s_or_b64 s[6:7], s[56:57], vcc
	s_and_b64 s[6:7], s[4:5], s[6:7]
	s_xor_b64 s[36:37], s[6:7], -1
	s_and_saveexec_b64 s[6:7], s[36:37]
	s_cbranch_execz .Lattn_ep_skip4
	v_lshl_add_u64 v[6:7], v[104:105], 1, s[16:17]
	global_store_dwordx4 v[6:7], v[0:3], off
; __device__ __forceinline__ unsigned cvt_pk_bf16(float lo, float hi) { unsigned r; asm volatile("v_cvt_pk_bf16_f32 %0, %1, %2" : "=v"(r) : "v"(lo), "v"(hi)); return r; }
; #define LAS __attribute__((address_space(3)))
; __device__ __forceinline__ void attn_phase(LAS unsigned char* lds, bf16_t* Qb, const bf16_t* KVb, const bf16_t* GZ, const float* sinkp) {
;     ...
;         for (int it = 0; it < 8; ++it) {
;             const int rr = cro + 4 * it, grow = mu ? NREAL + seq * 16 + (rr & 15) : row0 + rr;
;             const u32x4 ovv = *(const LAS u32x4*)(Wl + rr * 256 + ((cho ^ (rr & 15)) << 4));
;             const size_t goff = (size_t)grow * 2048 + head * 128 + cho * 8;
;             const u32x4 gz = *(const u32x4*)(GZ + goff);
;             float fo[8], fg[8]; unpack8(ovv, fo); unpack8(gz, fg);
;             u32x4 res; res.x = cvt_pk_bf16(fo[0] * fg[0], fo[1] * fg[1]); res.y = cvt_pk_bf16(fo[2] * fg[2], fo[3] * fg[3]); res.z = cvt_pk_bf16(fo[4] * fg[4], fo[5] * fg[5]); res.w = cvt_pk_bf16(fo[6] * fg[6], fo[7] * fg[7]);
;             if (!mu || (w < 4 && rr < 16)) *(u32x4*)(Qb + goff) = res;
;         }
.Lattn_ep_skip4:
	s_or_b64 exec, exec, s[6:7]
	s_waitcnt lgkmcnt(2)
	v_lshlrev_b32_e32 v16, 16, v132
	v_and_b32_e32 v132, 0xffff0000, v132
	v_lshlrev_b32_e32 v17, 16, v133
	v_and_b32_e32 v133, 0xffff0000, v133
	v_lshlrev_b32_e32 v18, 16, v134
	v_and_b32_e32 v134, 0xffff0000, v134
	v_lshlrev_b32_e32 v19, 16, v135
	v_and_b32_e32 v135, 0xffff0000, v135
	s_waitcnt vmcnt(2)
	v_lshlrev_b32_e32 v20, 16, v44
	v_and_b32_e32 v44, 0xffff0000, v44
	v_lshlrev_b32_e32 v21, 16, v45
	v_and_b32_e32 v45, 0xffff0000, v45
	v_lshlrev_b32_e32 v22, 16, v46
	v_and_b32_e32 v46, 0xffff0000, v46
	v_lshlrev_b32_e32 v23, 16, v47
	v_and_b32_e32 v47, 0xffff0000, v47
	v_mul_f32_e32 v0, v132, v44
	v_mul_f32_e32 v1, v133, v45
	v_mul_f32_e32 v2, v134, v46
	v_mul_f32_e32 v3, v135, v47
	v_mul_f32_e32 v16, v16, v20
	v_mul_f32_e32 v17, v17, v21
	v_mul_f32_e32 v18, v18, v22
	v_mul_f32_e32 v19, v19, v23
	v_cvt_pk_bf16_f32 v0, v16, v0
	v_cvt_pk_bf16_f32 v1, v17, v1
	v_cvt_pk_bf16_f32 v2, v18, v2
	v_cvt_pk_bf16_f32 v3, v19, v3
	v_add_u32_e32 v10, 20, v65
	v_cmp_lt_i32_e32 vcc, 15, v10
	s_or_b64 s[6:7], s[56:57], vcc
	s_and_b64 s[6:7], s[4:5], s[6:7]
	s_xor_b64 s[36:37], s[6:7], -1
	s_and_saveexec_b64 s[6:7], s[36:37]
	s_cbranch_execz .Lattn_ep_skip5
	v_lshl_add_u64 v[6:7], v[106:107], 1, s[16:17]
	global_store_dwordx4 v[6:7], v[0:3], off
.Lattn_ep_skip5:
	s_or_b64 exec, exec, s[6:7]
	s_waitcnt lgkmcnt(1)
	v_lshlrev_b32_e32 v16, 16, v136
	v_and_b32_e32 v136, 0xffff0000, v136
	v_lshlrev_b32_e32 v17, 16, v137
	v_and_b32_e32 v137, 0xffff0000, v137
	v_lshlrev_b32_e32 v18, 16, v138
	v_and_b32_e32 v138, 0xffff0000, v138
	v_lshlrev_b32_e32 v19, 16, v139
	v_and_b32_e32 v139, 0xffff0000, v139
	s_waitcnt vmcnt(1)
	v_lshlrev_b32_e32 v20, 16, v48
	v_and_b32_e32 v48, 0xffff0000, v48
	v_lshlrev_b32_e32 v21, 16, v49
	v_and_b32_e32 v49, 0xffff0000, v49
	v_lshlrev_b32_e32 v22, 16, v50
	v_and_b32_e32 v50, 0xffff0000, v50
	v_lshlrev_b32_e32 v23, 16, v51
	v_and_b32_e32 v51, 0xffff0000, v51
	v_mul_f32_e32 v0, v136, v48
	v_mul_f32_e32 v1, v137, v49
	v_mul_f32_e32 v2, v138, v50
	v_mul_f32_e32 v3, v139, v51
	v_mul_f32_e32 v16, v16, v20
	v_mul_f32_e32 v17, v17, v21
	v_mul_f32_e32 v18, v18, v22
	v_mul_f32_e32 v19, v19, v23
	v_cvt_pk_bf16_f32 v0, v16, v0
	v_cvt_pk_bf16_f32 v1, v17, v1
	v_cvt_pk_bf16_f32 v2, v18, v2
	v_cvt_pk_bf16_f32 v3, v19, v3
	v_add_u32_e32 v10, 24, v65
	v_cmp_lt_i32_e32 vcc, 15, v10
	s_or_b64 s[6:7], s[56:57], vcc
	s_and_b64 s[6:7], s[4:5], s[6:7]
	s_xor_b64 s[36:37], s[6:7], -1
	s_and_saveexec_b64 s[6:7], s[36:37]
	s_cbranch_execz .Lattn_ep_skip6
	v_lshl_add_u64 v[6:7], v[108:109], 1, s[16:17]
	global_store_dwordx4 v[6:7], v[0:3], off
.Lattn_ep_skip6:
	s_or_b64 exec, exec, s[6:7]
	s_waitcnt lgkmcnt(0)
	v_lshlrev_b32_e32 v16, 16, v140
	v_and_b32_e32 v140, 0xffff0000, v140
	v_lshlrev_b32_e32 v17, 16, v141
	v_and_b32_e32 v141, 0xffff0000, v141
	v_lshlrev_b32_e32 v18, 16, v142
	v_and_b32_e32 v142, 0xffff0000, v142
	v_lshlrev_b32_e32 v19, 16, v143
	v_and_b32_e32 v143, 0xffff0000, v143
	s_waitcnt vmcnt(0)
	v_lshlrev_b32_e32 v20, 16, v52
	v_and_b32_e32 v52, 0xffff0000, v52
	v_lshlrev_b32_e32 v21, 16, v53
	v_and_b32_e32 v53, 0xffff0000, v53
	v_lshlrev_b32_e32 v22, 16, v54
	v_and_b32_e32 v54, 0xffff0000, v54
	v_lshlrev_b32_e32 v23, 16, v55
	v_and_b32_e32 v55, 0xffff0000, v55
	v_mul_f32_e32 v0, v140, v52
	v_mul_f32_e32 v1, v141, v53
	v_mul_f32_e32 v2, v142, v54
	v_mul_f32_e32 v3, v143, v55
	v_mul_f32_e32 v16, v16, v20
	v_mul_f32_e32 v17, v17, v21
	v_mul_f32_e32 v18, v18, v22
	v_mul_f32_e32 v19, v19, v23
	v_cvt_pk_bf16_f32 v0, v16, v0
	v_cvt_pk_bf16_f32 v1, v17, v1
	v_cvt_pk_bf16_f32 v2, v18, v2
	v_cvt_pk_bf16_f32 v3, v19, v3
	v_add_u32_e32 v10, 28, v65
	v_cmp_lt_i32_e32 vcc, 15, v10
	s_or_b64 s[6:7], s[56:57], vcc
	s_and_b64 s[6:7], s[4:5], s[6:7]
	s_xor_b64 s[36:37], s[6:7], -1
	s_and_saveexec_b64 s[6:7], s[36:37]
	s_cbranch_execz .Lattn_ep_skip7
	v_lshl_add_u64 v[6:7], v[110:111], 1, s[16:17]
	global_store_dwordx4 v[6:7], v[0:3], off
.Lattn_ep_skip7:
	s_or_b64 exec, exec, s[6:7]
	s_branch .LBB0_153
